# v38 + forget-gate logits phase: all 32 operand loads issued up front (extra pieces in phase-dead v88-151), one wait, 16 MFMAs back to back (was 14 dependent L2 round trips)
# speedup vs baseline: 1.0045x; 1.0016x over previous
.LBB0_129:
	v_add_u32_e32 v4, s16, v24
	v_ashrrev_i32_e32 v5, 31, v4
	v_lshlrev_b64 v[4:5], 12, v[4:5]
	v_lshl_add_u64 v[86:87], v[16:17], 0, v[4:5]
	global_load_dwordx4 v[0:3], v[18:19], off
	global_load_dwordx4 v[30:33], v[18:19], off offset:32
	global_load_dwordx4 v[34:37], v[18:19], off offset:64
	global_load_dwordx4 v[38:41], v[18:19], off offset:96
	global_load_dwordx4 v[42:45], v[18:19], off offset:128
	global_load_dwordx4 v[46:49], v[18:19], off offset:160
	global_load_dwordx4 v[50:53], v[18:19], off offset:192
	global_load_dwordx4 v[4:7], v[86:87], off
	global_load_dwordx4 v[54:57], v[86:87], off offset:32
	global_load_dwordx4 v[58:61], v[18:19], off offset:224
	global_load_dwordx4 v[62:65], v[18:19], off offset:256
	global_load_dwordx4 v[66:69], v[18:19], off offset:288
	global_load_dwordx4 v[70:73], v[18:19], off offset:320
	global_load_dwordx4 v[74:77], v[18:19], off offset:352
	global_load_dwordx4 v[78:81], v[18:19], off offset:384
	global_load_dwordx4 v[82:85], v[18:19], off offset:416
	s_add_i32 s5, s5, s4
	global_load_dwordx4 v[88:91], v[86:87], off offset:64
	global_load_dwordx4 v[92:95], v[86:87], off offset:96
	global_load_dwordx4 v[96:99], v[86:87], off offset:128
	global_load_dwordx4 v[100:103], v[86:87], off offset:160
	global_load_dwordx4 v[104:107], v[86:87], off offset:192
	global_load_dwordx4 v[108:111], v[86:87], off offset:224
	global_load_dwordx4 v[112:115], v[86:87], off offset:256
	global_load_dwordx4 v[116:119], v[86:87], off offset:288
	global_load_dwordx4 v[120:123], v[86:87], off offset:320
	global_load_dwordx4 v[124:127], v[86:87], off offset:352
	global_load_dwordx4 v[128:131], v[86:87], off offset:384
	global_load_dwordx4 v[132:135], v[86:87], off offset:416
	global_load_dwordx4 v[136:139], v[86:87], off offset:448
	global_load_dwordx4 v[140:143], v[86:87], off offset:480
	global_load_dwordx4 v[144:147], v[18:19], off offset:448
	global_load_dwordx4 v[148:151], v[18:19], off offset:480
	s_waitcnt vmcnt(0)
	v_mfma_f32_32x32x16_bf16 v[0:15], v[4:7], v[0:3], 0
	v_mfma_f32_32x32x16_bf16 v[0:15], v[54:57], v[30:33], v[0:15]
	v_mfma_f32_32x32x16_bf16 v[0:15], v[88:91], v[34:37], v[0:15]
	v_mfma_f32_32x32x16_bf16 v[0:15], v[92:95], v[38:41], v[0:15]
	v_mfma_f32_32x32x16_bf16 v[0:15], v[96:99], v[42:45], v[0:15]
	v_mfma_f32_32x32x16_bf16 v[0:15], v[100:103], v[46:49], v[0:15]
	v_mfma_f32_32x32x16_bf16 v[0:15], v[104:107], v[50:53], v[0:15]
	v_mfma_f32_32x32x16_bf16 v[0:15], v[108:111], v[58:61], v[0:15]
	v_mfma_f32_32x32x16_bf16 v[0:15], v[112:115], v[62:65], v[0:15]
	v_mfma_f32_32x32x16_bf16 v[0:15], v[116:119], v[66:69], v[0:15]
	v_mfma_f32_32x32x16_bf16 v[0:15], v[120:123], v[70:73], v[0:15]
	v_mfma_f32_32x32x16_bf16 v[0:15], v[124:127], v[74:77], v[0:15]
	v_mfma_f32_32x32x16_bf16 v[0:15], v[128:131], v[78:81], v[0:15]
	v_mfma_f32_32x32x16_bf16 v[0:15], v[132:135], v[82:85], v[0:15]
	v_mfma_f32_32x32x16_bf16 v[0:15], v[136:139], v[144:147], v[0:15]
	v_mfma_f32_32x32x16_bf16 v[0:15], v[140:143], v[148:151], v[0:15]
	s_nop 11
	ds_write2st64_b32 v29, v0, v1 offset1:1
	ds_write2st64_b32 v29, v2, v3 offset0:2 offset1:3
	ds_write2st64_b32 v29, v4, v5 offset0:4 offset1:5
	ds_write2st64_b32 v29, v6, v7 offset0:6 offset1:7
	ds_write2st64_b32 v29, v8, v9 offset0:8 offset1:9
	ds_write2st64_b32 v29, v10, v11 offset0:10 offset1:11
	ds_write2st64_b32 v29, v12, v13 offset0:12 offset1:13
	ds_write2st64_b32 v29, v14, v15 offset0:14 offset1:15
	s_waitcnt lgkmcnt(0)
	s_barrier
	global_load_dword v32, v[20:21], off
	v_add_u32_e32 v1, s16, v28
	v_and_or_b32 v2, v1, s10, v25
	v_lshlrev_b32_e32 v160, 2, v2
	ds_read2st64_b32 v[2:3], v26 offset1:8
	ds_read2st64_b32 v[4:5], v26 offset0:16 offset1:24
	ds_read2st64_b32 v[6:7], v26 offset0:32 offset1:40
	ds_read2st64_b32 v[8:9], v26 offset0:48 offset1:56
	ds_read2st64_b32 v[10:11], v26 offset0:64 offset1:72
	ds_read2st64_b32 v[12:13], v26 offset0:80 offset1:88
	ds_read2st64_b32 v[14:15], v26 offset0:96 offset1:104
	ds_read2st64_b32 v[30:31], v26 offset0:112 offset1:120
	s_waitcnt lgkmcnt(7)
	v_add_f32_e32 v2, 0, v2
	s_waitcnt lgkmcnt(6)
	v_add_f32_e32 v2, v2, v4
	s_waitcnt lgkmcnt(5)
	v_add_f32_e32 v2, v2, v6
	s_waitcnt lgkmcnt(4)
	v_add_f32_e32 v2, v2, v8
	s_waitcnt lgkmcnt(3)
	v_add_f32_e32 v2, v2, v10
	s_waitcnt lgkmcnt(2)
	v_add_f32_e32 v2, v2, v12
	s_waitcnt lgkmcnt(1)
	v_add_f32_e32 v2, v2, v14
	s_waitcnt lgkmcnt(0)
	v_add_f32_e32 v2, v2, v30
	v_ashrrev_i32_e32 v0, 11, v1
	v_ashrrev_i32_e32 v1, 31, v0
	v_lshlrev_b64 v[0:1], 18, v[0:1]
	v_lshl_add_u64 v[0:1], v[22:23], 0, v[0:1]
	v_lshl_add_u64 v[0:1], v[0:1], 0, v[160:161]
	v_add_f32_e32 v3, 0, v3
	v_add_f32_e32 v3, v3, v5
	v_add_f32_e32 v3, v3, v7
	v_add_f32_e32 v3, v3, v9
	v_add_f32_e32 v3, v3, v11
	v_add_f32_e32 v3, v3, v13
	v_add_f32_e32 v3, v3, v15
	v_add_f32_e32 v3, v3, v31
	s_waitcnt vmcnt(0)
	v_add_f32_e32 v2, v2, v32
	v_min_f32_e32 v4, 0, v2
	v_mul_f32_e64 v2, |v2|, s6
	v_exp_f32_e32 v2, v2
	s_nop 0
	v_add_f32_e32 v2, 1.0, v2
	v_log_f32_e32 v2, v2
	s_nop 0
	v_fma_f32 v2, v4, s7, -v2
	global_store_dword v[0:1], v2, off
	global_load_dword v2, v[20:21], off
	v_add_u32_e32 v1, s16, v27
	v_ashrrev_i32_e32 v0, 11, v1
	v_and_or_b32 v4, v1, s10, v25
	v_ashrrev_i32_e32 v1, 31, v0
	v_lshlrev_b64 v[0:1], 18, v[0:1]
	s_add_i32 s16, s16, s17
	v_lshl_add_u64 v[0:1], v[22:23], 0, v[0:1]
	v_lshlrev_b32_e32 v160, 2, v4
	s_cmpk_lt_i32 s5, 0x100
	v_lshl_add_u64 v[0:1], v[0:1], 0, v[160:161]
	s_waitcnt vmcnt(0)
	v_add_f32_e32 v2, v3, v2
	v_min_f32_e32 v3, 0, v2
	v_mul_f32_e64 v2, |v2|, s6
	v_exp_f32_e32 v2, v2
	s_nop 0
	v_add_f32_e32 v2, 1.0, v2
	v_log_f32_e32 v2, v2
	s_nop 0
	v_fma_f32 v2, v3, s7, -v2
	global_store_dword v[0:1], v2, off
	s_barrier
	s_cbranch_scc1 .LBB0_129
